# weight-conversion loop: counted vmcnt ladder (next item's 32 loads stay in flight) plus vmcnt(4) before issuing the following item; removes two full drains per iteration
# speedup vs baseline: 1.0071x; 1.0071x over previous
; #define LAS __attribute__((address_space(3)))
; __device__ __forceinline__ void cvt_store(const CvtJob& j, CvtRegs& R, LAS float* scr, int lane) {
;     const int nblk = j.N >> 5, kb = j.item / nblk, nb = j.item - kb * nblk, k0 = kb * 64, n0 = nb * 32, mode = j.mode, K = j.K;
; #pragma unroll
;     for (int i = 0; i < 32; ++i) scr[(2 * i + (lane >> 5)) * 33 + (lane & 31)] = R.vv[i];
.Lcv_ok1:
	s_lshr_b32 s24, s24, 5
	v_cvt_f32_u32_e32 v24, s24
	s_sub_i32 s75, 0, s24
	s_abs_i32 s74, s1
	s_ashr_i32 s26, s1, 31
	v_rcp_iflag_f32_e32 v24, v24
	v_add_u32_e32 v99, 0x400, v61
	v_add_u32_e32 v100, 0x800, v61
	v_add_u32_e32 v101, 0xc00, v61
	v_mul_f32_e32 v24, 0x4f7ffffe, v24
	v_cvt_u32_f32_e32 v24, v24
	v_add_u32_e32 v102, 0x1000, v61
	v_add_u32_e32 v103, 0x1400, v61
	v_add_u32_e32 v104, 0x1800, v61
	v_readfirstlane_b32 s76, v24
	s_mul_i32 s75, s75, s76
	s_mul_hi_u32 s75, s76, s75
	s_add_i32 s76, s76, s75
	s_mul_hi_u32 s75, s74, s76
	s_mul_i32 s76, s75, s24
	s_sub_i32 s74, s74, s76
	s_add_i32 s77, s75, 1
	s_sub_i32 s76, s74, s24
	s_cmp_ge_u32 s74, s24
	s_cselect_b32 s75, s77, s75
	s_cselect_b32 s74, s76, s74
	s_add_i32 s76, s75, 1
	s_cmp_ge_u32 s74, s24
	s_cselect_b32 s74, s76, s75
	s_xor_b32 s74, s74, s26
	v_add_u32_e32 v105, 0x1c00, v61
	s_sub_i32 s26, s74, s26
	s_waitcnt vmcnt(62)
	ds_write2_b32 v61, v23, v25 offset1:66
	s_waitcnt vmcnt(60)
	ds_write2_b32 v61, v26, v27 offset0:132 offset1:198
	s_waitcnt vmcnt(58)
	ds_write2_b32 v99, v28, v29 offset0:8 offset1:74
	s_waitcnt vmcnt(56)
	ds_write2_b32 v99, v30, v31 offset0:140 offset1:206
	s_waitcnt vmcnt(54)
	ds_write2_b32 v100, v32, v33 offset0:16 offset1:82
	s_waitcnt vmcnt(52)
	ds_write2_b32 v100, v34, v35 offset0:148 offset1:214
	s_waitcnt vmcnt(50)
	ds_write2_b32 v101, v36, v37 offset0:24 offset1:90
	s_waitcnt vmcnt(48)
	ds_write2_b32 v101, v38, v39 offset0:156 offset1:222
	s_waitcnt vmcnt(46)
	ds_write2_b32 v102, v40, v41 offset0:32 offset1:98
	s_waitcnt vmcnt(44)
	ds_write2_b32 v102, v42, v43 offset0:164 offset1:230
	s_waitcnt vmcnt(42)
	ds_write2_b32 v103, v44, v45 offset0:40 offset1:106
	s_waitcnt vmcnt(40)
	ds_write2_b32 v103, v46, v47 offset0:172 offset1:238
	s_waitcnt vmcnt(38)
	ds_write2_b32 v104, v48, v49 offset0:48 offset1:114
	s_waitcnt vmcnt(36)
	ds_write2_b32 v104, v50, v51 offset0:180 offset1:246
	s_waitcnt vmcnt(34)
	ds_write2_b32 v105, v52, v53 offset0:56 offset1:122
	s_waitcnt vmcnt(32)
	ds_write2_b32 v105, v54, v55 offset0:188 offset1:254
	s_branch .Lcv_join

; #define LAS __attribute__((address_space(3)))
; __device__ __forceinline__ void lds_wait() { asm volatile("s_waitcnt lgkmcnt(0)" ::: "memory"); }
; __device__ __forceinline__ void cvt_store(const CvtJob& j, CvtRegs& R, LAS float* scr, int lane) {
;     const int nblk = j.N >> 5, kb = j.item / nblk, nb = j.item - kb * nblk, k0 = kb * 64, n0 = nb * 32, mode = j.mode, K = j.K;
; #pragma unroll
;     for (int i = 0; i < 32; ++i) scr[(2 * i + (lane >> 5)) * 33 + (lane & 31)] = R.vv[i];
;     lds_wait();
;     const int c = lane & 7;
; #pragma unroll
;     for (int jj = 0; jj < 4; ++jj) { const int n = (lane >> 3) + 8 * jj, col = n0 + n; const LAS float* sp = scr + (8 * c) * 33 + n;
;         float cs = 1.f; int dest = col;
;         if (mode == 1) { cs = (col >= 1024 && col < 2048) ? 0.08838834764831845f : 1.f; }
;         else if (mode == 2) { const int nn = col >= 5632 ? 1 : 0, ch = col - nn * 5632; dest = 256 * (ch >> 7) + 128 * nn + (ch & 127); }
;         else if (mode == 3) { const int nn = col >= 256 ? 1 : 0, ch = col - nn * 256; dest = 256 * (ch >> 7) + 128 * nn + (ch & 127); }
.Lcv_join:
	s_mul_i32 s24, s26, s24
	s_waitcnt lgkmcnt(0)
	s_sub_i32 s24, s1, s24
	s_lshl_b32 s24, s24, 5
	v_add_u32_e32 v107, s24, v56
	s_cmp_lt_i32 s3, 2
	s_mov_b64 s[74:75], -1
	s_cbranch_scc1 .LBB0_109
	s_cmp_gt_i32 s3, 2
	v_and_b32_e32 v24, 0x7f, v107
	s_cbranch_scc0 .LBB0_106
	v_cmp_lt_i32_e32 vcc, s81, v107
	s_mov_b64 s[74:75], 0
	s_nop 0
	v_cndmask_b32_e32 v106, 0, v62, vcc
	v_add_lshl_u32 v106, v106, v107, 1
	v_and_b32_e32 v106, 0xffffff00, v106
	v_cndmask_b32_e32 v108, 0, v63, vcc
	v_or3_b32 v106, v108, v24, v106

; __device__ __forceinline__ unsigned cvt_pk_bf16(float lo, float hi) { unsigned r; asm volatile("v_cvt_pk_bf16_f32 %0, %1, %2" : "=v"(r) : "v"(lo), "v"(hi)); return r; }
; #define LAS __attribute__((address_space(3)))
; __device__ __forceinline__ void lds_wait() { asm volatile("s_waitcnt lgkmcnt(0)" ::: "memory"); }
; __device__ __forceinline__ void cvt_store(const CvtJob& j, CvtRegs& R, LAS float* scr, int lane) {
;     ...
;     for (int jj = 0; jj < 4; ++jj) { const int n = (lane >> 3) + 8 * jj, col = n0 + n; const LAS float* sp = scr + (8 * c) * 33 + n;
;         float cs = 1.f; int dest = col;
;         if (mode == 1) { cs = (col >= 1024 && col < 2048) ? 0.08838834764831845f : 1.f; }
;         else if (mode == 2) { const int nn = col >= 5632 ? 1 : 0, ch = col - nn * 5632; dest = 256 * (ch >> 7) + 128 * nn + (ch & 127); }
;         else if (mode == 3) { const int nn = col >= 256 ? 1 : 0, ch = col - nn * 256; dest = 256 * (ch >> 7) + 128 * nn + (ch & 127); }
;         const f32x4 g0 = R.g0 * cs, g1 = R.g1 * cs;
;         u32x4 o; o.x = cvt_pk_bf16(sp[0 * 33] * g0[0], sp[1 * 33] * g0[1]); o.y = cvt_pk_bf16(sp[2 * 33] * g0[2], sp[3 * 33] * g0[3]); o.z = cvt_pk_bf16(sp[4 * 33] * g1[0], sp[5 * 33] * g1[1]); o.w = cvt_pk_bf16(sp[6 * 33] * g1[2], sp[7 * 33] * g1[3]);
;         *(u32x4*)(j.WT + (size_t)dest * K + k0 + 8 * c) = o; }
;     lds_wait();
.LBB0_143:
	ds_read2_b32 v[108:109], v57 offset0:24 offset1:57
	v_pk_mul_f32 v[110:111], v[6:7], v[24:25] op_sel_hi:[1,0]
	v_pk_mul_f32 v[112:113], v[8:9], v[24:25] op_sel_hi:[1,0]
	v_pk_mul_f32 v[114:115], v[2:3], v[24:25] op_sel_hi:[1,0]
	v_mul_lo_u32 v116, s23, v106
	s_waitcnt lgkmcnt(0)
	v_mul_f32_e32 v107, v108, v110
	v_mul_f32_e32 v108, v109, v111
	v_cvt_pk_bf16_f32 v108, v107, v108
	ds_read2_b32 v[110:111], v57 offset0:90 offset1:123
	s_and_b64 vcc, exec, s[4:5]
	s_mov_b64 s[4:5], -1
	s_waitcnt lgkmcnt(0)
	v_mul_f32_e32 v109, v113, v111
	v_mul_f32_e32 v107, v112, v110
	v_cvt_pk_bf16_f32 v109, v107, v109
	ds_read2_b32 v[110:111], v57 offset0:156 offset1:189
	v_pk_mul_f32 v[112:113], v[4:5], v[24:25] op_sel_hi:[1,0]
	v_ashrrev_i32_e32 v24, 31, v106
	v_mul_lo_u32 v24, s22, v24
	s_waitcnt lgkmcnt(0)
	v_mul_f32_e32 v107, v114, v110
	v_mul_f32_e32 v110, v115, v111
	v_cvt_pk_bf16_f32 v110, v107, v110
	ds_read2_b32 v[114:115], v57 offset0:222 offset1:255
	v_mad_u64_u32 v[106:107], s[76:77], s22, v106, 0
	v_add3_u32 v107, v107, v24, v116
	v_lshl_add_u64 v[106:107], v[106:107], 1, s[20:21]
	v_lshl_add_u64 v[106:107], s[74:75], 1, v[106:107]
	s_waitcnt lgkmcnt(0)
	v_mul_f32_e32 v111, v112, v114
	v_lshl_add_u64 v[106:107], v[106:107], 0, v[20:21]
	v_mul_f32_e32 v112, v113, v115
	v_cvt_pk_bf16_f32 v111, v111, v112
	global_store_dwordx4 v[106:107], v[108:111], off
	s_waitcnt vmcnt(4)
	s_waitcnt lgkmcnt(0)
	s_cbranch_vccnz .LBB0_69
	s_add_i32 s0, s0, s25
	s_add_i32 s87, s45, s80
	s_cmpk_lt_i32 s87, 0x1800
	s_movk_i32 s24, 0x1800
	s_cbranch_scc1 .LBB0_156
	s_cmpk_gt_u32 s87, 0x1fff
	s_cbranch_scc0 .LBB0_157
	s_cmpk_gt_u32 s87, 0x4bff
	s_cbranch_scc0 .LBB0_158
	s_cmpk_gt_u32 s87, 0x77ff
	s_mov_b64 s[78:79], -1
	s_cbranch_scc0 .LBB0_169
	s_cmpk_gt_u32 s87, 0x8dff
	s_cbranch_scc0 .LBB0_159
	s_cmpk_gt_u32 s87, 0xa3ff
	s_cbranch_scc0 .LBB0_164
	s_cmpk_gt_u32 s87, 0xb3ff
	s_cbranch_scc0 .LBB0_162
	s_cmpk_gt_u32 s87, 0xb5ff
	s_mov_b64 s[22:23], -1
	s_cbranch_scc0 .LBB0_154
	s_mov_b64 s[22:23], 0
	s_cmpk_gt_u32 s87, 0xbdff
	s_mov_b64 s[4:5], 0
	s_cbranch_scc1 .LBB0_154
	s_add_i32 s1, s87, 0xffff4a00
	s_mov_b64 s[4:5], -1
	s_mov_b64 s[6:7], s[8:9]
	s_mov_b64 s[20:21], s[30:31]

; __device__ __forceinline__ unsigned cvt_pk_bf16(float lo, float hi) { unsigned r; asm volatile("v_cvt_pk_bf16_f32 %0, %1, %2" : "=v"(r) : "v"(lo), "v"(hi)); return r; }
; #define LAS __attribute__((address_space(3)))
; __device__ __forceinline__ void cvt_store(const CvtJob& j, CvtRegs& R, LAS float* scr, int lane) {
;     ...
;     const int c = lane & 7;
; #pragma unroll
;     for (int jj = 0; jj < 4; ++jj) { const int n = (lane >> 3) + 8 * jj, col = n0 + n; const LAS float* sp = scr + (8 * c) * 33 + n;
;         float cs = 1.f; int dest = col;
;         if (mode == 1) { cs = (col >= 1024 && col < 2048) ? 0.08838834764831845f : 1.f; }
;         else if (mode == 2) { const int nn = col >= 5632 ? 1 : 0, ch = col - nn * 5632; dest = 256 * (ch >> 7) + 128 * nn + (ch & 127); }
;         else if (mode == 3) { const int nn = col >= 256 ? 1 : 0, ch = col - nn * 256; dest = 256 * (ch >> 7) + 128 * nn + (ch & 127); }
;         const f32x4 g0 = R.g0 * cs, g1 = R.g1 * cs;
;         u32x4 o; o.x = cvt_pk_bf16(sp[0 * 33] * g0[0], sp[1 * 33] * g0[1]); o.y = cvt_pk_bf16(sp[2 * 33] * g0[2], sp[3 * 33] * g0[3]); o.z = cvt_pk_bf16(sp[4 * 33] * g1[0], sp[5 * 33] * g1[1]); o.w = cvt_pk_bf16(sp[6 * 33] * g1[2], sp[7 * 33] * g1[3]);
;         *(u32x4*)(j.WT + (size_t)dest * K + k0 + 8 * c) = o; }
.LBB0_189:
	ds_read2_b32 v[100:101], v57 offset1:33
	v_pk_mul_f32 v[102:103], v[10:11], v[24:25] op_sel_hi:[1,0]
	v_pk_mul_f32 v[104:105], v[12:13], v[24:25] op_sel_hi:[1,0]
	v_pk_mul_f32 v[106:107], v[14:15], v[24:25] op_sel_hi:[1,0]
	s_lshl_b32 s74, s76, 6
	s_waitcnt lgkmcnt(0)
	v_mul_f32_e32 v99, v100, v102
	v_mul_f32_e32 v100, v101, v103
	v_cvt_pk_bf16_f32 v100, v99, v100
	ds_read2_b32 v[102:103], v57 offset0:66 offset1:99
	v_mul_lo_u32 v108, s73, v98
	s_ashr_i32 s75, s74, 31
	s_cmp_lt_i32 s85, 2
	s_waitcnt lgkmcnt(0)
	v_mul_f32_e32 v101, v105, v103
	v_mul_f32_e32 v99, v104, v102
	v_cvt_pk_bf16_f32 v101, v99, v101
	ds_read2_b32 v[102:103], v57 offset0:132 offset1:165
	v_pk_mul_f32 v[104:105], v[16:17], v[24:25] op_sel_hi:[1,0]
	s_waitcnt lgkmcnt(0)
	v_mul_f32_e32 v24, v106, v102
	v_mul_f32_e32 v99, v107, v103
	v_cvt_pk_bf16_f32 v102, v24, v99
	ds_read2_b32 v[106:107], v57 offset0:198 offset1:231
	v_ashrrev_i32_e32 v24, 31, v98
	v_mul_lo_u32 v24, s72, v24
	s_waitcnt lgkmcnt(0)
	v_mul_f32_e32 v99, v104, v106
	v_mul_f32_e32 v103, v105, v107
	v_cvt_pk_bf16_f32 v103, v99, v103
	v_mad_u64_u32 v[98:99], s[76:77], s72, v98, 0
	v_add3_u32 v99, v99, v24, v108
	v_lshl_add_u64 v[98:99], v[98:99], 1, s[70:71]
	v_lshl_add_u64 v[98:99], s[74:75], 1, v[98:99]
	v_lshl_add_u64 v[98:99], v[98:99], 0, v[20:21]
	global_store_dwordx4 v[98:99], v[100:103], off
	v_add_u32_e32 v99, s26, v58
	s_mov_b64 s[76:77], -1
	s_cbranch_scc1 .LBB0_195
	s_cmp_gt_i32 s85, 2
	v_and_b32_e32 v24, 0x7f, v99
	s_cbranch_scc0 .LBB0_192
	v_cmp_lt_i32_e32 vcc, s81, v99
	s_mov_b64 s[76:77], 0
	s_nop 0
	v_cndmask_b32_e32 v98, 0, v62, vcc
	v_add_lshl_u32 v98, v98, v99, 1
	v_and_b32_e32 v98, 0xffffff00, v98
	v_cndmask_b32_e32 v100, 0, v63, vcc
	v_or3_b32 v98, v100, v24, v98
